# GLA scan loop hand-pipelined: next 4 chunk steps loads in flight with counted vmcnt
# speedup vs baseline: 1.0052x; 1.0034x over previous
.LBB0_555:
	v_ashrrev_i32_e32 v0, 17, v28
	s_mov_b32 s7, 0x20000
	v_ashrrev_i32_e32 v1, 31, v0
	v_cmp_gt_u32_e32 vcc, s7, v28
	v_lshlrev_b64 v[10:11], 10, v[0:1]
	v_lshrrev_b32_e32 v0, 7, v28
	s_movk_i32 s7, 0x3e0
	v_and_or_b32 v10, v0, s7, v10
	v_lshlrev_b32_e32 v0, 4, v28
	v_and_b32_e32 v8, 0xfff0, v0
	v_lshlrev_b32_e32 v0, 5, v28
	v_lshl_add_u64 v[12:13], s[46:47], 0, v[8:9]
	v_and_b32_e32 v8, 0x1e0, v0
	v_lshl_add_u64 v[14:15], s[14:15], 0, v[8:9]
	v_mov_b32_e32 v40, 31
	v_cndmask_b32_e32 v8, v40, v9, vcc
	v_lshl_add_u64 v[40:41], v[10:11], 0, v[8:9]
	v_lshlrev_b64 v[42:43], 16, v[40:41]
	v_lshl_add_u64 v[42:43], v[12:13], 0, v[42:43]
	v_lshlrev_b64 v[44:45], 9, v[40:41]
	v_lshl_add_u64 v[44:45], v[14:15], 0, v[44:45]
	v_mov_b32_e32 v46, 0x10000
	v_mov_b32_e32 v47, 0
	v_mov_b32_e32 v48, 0xffff0000
	v_mov_b32_e32 v49, -1
	v_cndmask_b32_e32 v46, v48, v46, vcc
	v_cndmask_b32_e32 v47, v49, v47, vcc
	v_mov_b32_e32 v50, 0x200
	v_mov_b32_e32 v51, 0
	v_mov_b32_e32 v48, 0xfffffe00
	v_cndmask_b32_e32 v50, v48, v50, vcc
	v_cndmask_b32_e32 v51, v49, v51, vcc
	v_mov_b64_e32 v[100:101], v[42:43]
	v_mov_b32_e32 v104, 0
	v_mov_b32_e32 v105, 0
	v_mov_b32_e32 v106, 0
	v_mov_b32_e32 v107, 0
	v_mov_b32_e32 v108, 0
	v_mov_b32_e32 v109, 0
	v_mov_b32_e32 v110, 0
	v_mov_b32_e32 v111, 0
	global_load_dwordx4 v[52:55], v[42:43], off
	global_load_dwordx4 v[56:59], v[44:45], off
	global_load_dwordx4 v[60:63], v[44:45], off offset:16
	v_lshl_add_u64 v[42:43], v[42:43], 0, v[46:47]
	v_lshl_add_u64 v[44:45], v[44:45], 0, v[50:51]
	global_load_dwordx4 v[64:67], v[42:43], off
	global_load_dwordx4 v[68:71], v[44:45], off
	global_load_dwordx4 v[72:75], v[44:45], off offset:16
	v_lshl_add_u64 v[42:43], v[42:43], 0, v[46:47]
	v_lshl_add_u64 v[44:45], v[44:45], 0, v[50:51]
	global_load_dwordx4 v[76:79], v[42:43], off
	global_load_dwordx4 v[80:83], v[44:45], off
	global_load_dwordx4 v[84:87], v[44:45], off offset:16
	v_lshl_add_u64 v[42:43], v[42:43], 0, v[46:47]
	v_lshl_add_u64 v[44:45], v[44:45], 0, v[50:51]
	global_load_dwordx4 v[88:91], v[42:43], off
	global_load_dwordx4 v[92:95], v[44:45], off
	global_load_dwordx4 v[96:99], v[44:45], off offset:16
	v_lshl_add_u64 v[42:43], v[42:43], 0, v[46:47]
	v_lshl_add_u64 v[44:45], v[44:45], 0, v[50:51]
	v_cvt_pk_bf16_f32 v112, v104, v105
	v_cvt_pk_bf16_f32 v113, v106, v107
	v_cvt_pk_bf16_f32 v114, v108, v109
	v_cvt_pk_bf16_f32 v115, v110, v111
	s_waitcnt vmcnt(9)
	global_store_dwordx4 v[100:101], v[112:115], off
	v_lshlrev_b32_e32 v116, 16, v52
	v_and_b32_e32 v117, 0xffff0000, v52
	v_lshlrev_b32_e32 v118, 16, v53
	v_and_b32_e32 v119, 0xffff0000, v53
	v_lshlrev_b32_e32 v120, 16, v54
	v_and_b32_e32 v121, 0xffff0000, v54
	v_lshlrev_b32_e32 v122, 16, v55
	v_and_b32_e32 v123, 0xffff0000, v55
	v_pk_fma_f32 v[104:105], v[104:105], v[56:57], v[116:117]
	v_pk_fma_f32 v[106:107], v[106:107], v[58:59], v[118:119]
	v_pk_fma_f32 v[108:109], v[108:109], v[60:61], v[120:121]
	v_pk_fma_f32 v[110:111], v[110:111], v[62:63], v[122:123]
	v_lshl_add_u64 v[100:101], v[100:101], 0, v[46:47]
	global_load_dwordx4 v[52:55], v[42:43], off
	global_load_dwordx4 v[56:59], v[44:45], off
	global_load_dwordx4 v[60:63], v[44:45], off offset:16
	v_lshl_add_u64 v[42:43], v[42:43], 0, v[46:47]
	v_lshl_add_u64 v[44:45], v[44:45], 0, v[50:51]
	v_cvt_pk_bf16_f32 v112, v104, v105
	v_cvt_pk_bf16_f32 v113, v106, v107
	v_cvt_pk_bf16_f32 v114, v108, v109
	v_cvt_pk_bf16_f32 v115, v110, v111
	s_waitcnt vmcnt(10)
	global_store_dwordx4 v[100:101], v[112:115], off
	v_lshlrev_b32_e32 v116, 16, v64
	v_and_b32_e32 v117, 0xffff0000, v64
	v_lshlrev_b32_e32 v118, 16, v65
	v_and_b32_e32 v119, 0xffff0000, v65
	v_lshlrev_b32_e32 v120, 16, v66
	v_and_b32_e32 v121, 0xffff0000, v66
	v_lshlrev_b32_e32 v122, 16, v67
	v_and_b32_e32 v123, 0xffff0000, v67
	v_pk_fma_f32 v[104:105], v[104:105], v[68:69], v[116:117]
	v_pk_fma_f32 v[106:107], v[106:107], v[70:71], v[118:119]
	v_pk_fma_f32 v[108:109], v[108:109], v[72:73], v[120:121]
	v_pk_fma_f32 v[110:111], v[110:111], v[74:75], v[122:123]
	v_lshl_add_u64 v[100:101], v[100:101], 0, v[46:47]
	global_load_dwordx4 v[64:67], v[42:43], off
	global_load_dwordx4 v[68:71], v[44:45], off
	global_load_dwordx4 v[72:75], v[44:45], off offset:16
	v_lshl_add_u64 v[42:43], v[42:43], 0, v[46:47]
	v_lshl_add_u64 v[44:45], v[44:45], 0, v[50:51]
	v_cvt_pk_bf16_f32 v112, v104, v105
	v_cvt_pk_bf16_f32 v113, v106, v107
	v_cvt_pk_bf16_f32 v114, v108, v109
	v_cvt_pk_bf16_f32 v115, v110, v111
	s_waitcnt vmcnt(11)
	global_store_dwordx4 v[100:101], v[112:115], off
	v_lshlrev_b32_e32 v116, 16, v76
	v_and_b32_e32 v117, 0xffff0000, v76
	v_lshlrev_b32_e32 v118, 16, v77
	v_and_b32_e32 v119, 0xffff0000, v77
	v_lshlrev_b32_e32 v120, 16, v78
	v_and_b32_e32 v121, 0xffff0000, v78
	v_lshlrev_b32_e32 v122, 16, v79
	v_and_b32_e32 v123, 0xffff0000, v79
	v_pk_fma_f32 v[104:105], v[104:105], v[80:81], v[116:117]
	v_pk_fma_f32 v[106:107], v[106:107], v[82:83], v[118:119]
	v_pk_fma_f32 v[108:109], v[108:109], v[84:85], v[120:121]
	v_pk_fma_f32 v[110:111], v[110:111], v[86:87], v[122:123]
	v_lshl_add_u64 v[100:101], v[100:101], 0, v[46:47]
	global_load_dwordx4 v[76:79], v[42:43], off
	global_load_dwordx4 v[80:83], v[44:45], off
	global_load_dwordx4 v[84:87], v[44:45], off offset:16
	v_lshl_add_u64 v[42:43], v[42:43], 0, v[46:47]
	v_lshl_add_u64 v[44:45], v[44:45], 0, v[50:51]
	v_cvt_pk_bf16_f32 v112, v104, v105
	v_cvt_pk_bf16_f32 v113, v106, v107
	v_cvt_pk_bf16_f32 v114, v108, v109
	v_cvt_pk_bf16_f32 v115, v110, v111
	s_waitcnt vmcnt(12)
	global_store_dwordx4 v[100:101], v[112:115], off
	v_lshlrev_b32_e32 v116, 16, v88
	v_and_b32_e32 v117, 0xffff0000, v88
	v_lshlrev_b32_e32 v118, 16, v89
	v_and_b32_e32 v119, 0xffff0000, v89
	v_lshlrev_b32_e32 v120, 16, v90
	v_and_b32_e32 v121, 0xffff0000, v90
	v_lshlrev_b32_e32 v122, 16, v91
	v_and_b32_e32 v123, 0xffff0000, v91
	v_pk_fma_f32 v[104:105], v[104:105], v[92:93], v[116:117]
	v_pk_fma_f32 v[106:107], v[106:107], v[94:95], v[118:119]
	v_pk_fma_f32 v[108:109], v[108:109], v[96:97], v[120:121]
	v_pk_fma_f32 v[110:111], v[110:111], v[98:99], v[122:123]
	v_lshl_add_u64 v[100:101], v[100:101], 0, v[46:47]
	global_load_dwordx4 v[88:91], v[42:43], off
	global_load_dwordx4 v[92:95], v[44:45], off
	global_load_dwordx4 v[96:99], v[44:45], off offset:16
	v_lshl_add_u64 v[42:43], v[42:43], 0, v[46:47]
	v_lshl_add_u64 v[44:45], v[44:45], 0, v[50:51]
	s_mov_b32 s7, 7
.Lscan_pipe:
	v_cvt_pk_bf16_f32 v112, v104, v105
	v_cvt_pk_bf16_f32 v113, v106, v107
	v_cvt_pk_bf16_f32 v114, v108, v109
	v_cvt_pk_bf16_f32 v115, v110, v111
	s_waitcnt vmcnt(12)
	global_store_dwordx4 v[100:101], v[112:115], off
	v_lshlrev_b32_e32 v116, 16, v52
	v_and_b32_e32 v117, 0xffff0000, v52
	v_lshlrev_b32_e32 v118, 16, v53
	v_and_b32_e32 v119, 0xffff0000, v53
	v_lshlrev_b32_e32 v120, 16, v54
	v_and_b32_e32 v121, 0xffff0000, v54
	v_lshlrev_b32_e32 v122, 16, v55
	v_and_b32_e32 v123, 0xffff0000, v55
	v_pk_fma_f32 v[104:105], v[104:105], v[56:57], v[116:117]
	v_pk_fma_f32 v[106:107], v[106:107], v[58:59], v[118:119]
	v_pk_fma_f32 v[108:109], v[108:109], v[60:61], v[120:121]
	v_pk_fma_f32 v[110:111], v[110:111], v[62:63], v[122:123]
	v_lshl_add_u64 v[100:101], v[100:101], 0, v[46:47]
	global_load_dwordx4 v[52:55], v[42:43], off
	global_load_dwordx4 v[56:59], v[44:45], off
	global_load_dwordx4 v[60:63], v[44:45], off offset:16
	v_lshl_add_u64 v[42:43], v[42:43], 0, v[46:47]
	v_lshl_add_u64 v[44:45], v[44:45], 0, v[50:51]
	v_cvt_pk_bf16_f32 v112, v104, v105
	v_cvt_pk_bf16_f32 v113, v106, v107
	v_cvt_pk_bf16_f32 v114, v108, v109
	v_cvt_pk_bf16_f32 v115, v110, v111
	s_waitcnt vmcnt(12)
	global_store_dwordx4 v[100:101], v[112:115], off
	v_lshlrev_b32_e32 v116, 16, v64
	v_and_b32_e32 v117, 0xffff0000, v64
	v_lshlrev_b32_e32 v118, 16, v65
	v_and_b32_e32 v119, 0xffff0000, v65
	v_lshlrev_b32_e32 v120, 16, v66
	v_and_b32_e32 v121, 0xffff0000, v66
	v_lshlrev_b32_e32 v122, 16, v67
	v_and_b32_e32 v123, 0xffff0000, v67
	v_pk_fma_f32 v[104:105], v[104:105], v[68:69], v[116:117]
	v_pk_fma_f32 v[106:107], v[106:107], v[70:71], v[118:119]
	v_pk_fma_f32 v[108:109], v[108:109], v[72:73], v[120:121]
	v_pk_fma_f32 v[110:111], v[110:111], v[74:75], v[122:123]
	v_lshl_add_u64 v[100:101], v[100:101], 0, v[46:47]
	global_load_dwordx4 v[64:67], v[42:43], off
	global_load_dwordx4 v[68:71], v[44:45], off
	global_load_dwordx4 v[72:75], v[44:45], off offset:16
	v_lshl_add_u64 v[42:43], v[42:43], 0, v[46:47]
	v_lshl_add_u64 v[44:45], v[44:45], 0, v[50:51]
	v_cvt_pk_bf16_f32 v112, v104, v105
	v_cvt_pk_bf16_f32 v113, v106, v107
	v_cvt_pk_bf16_f32 v114, v108, v109
	v_cvt_pk_bf16_f32 v115, v110, v111
	s_waitcnt vmcnt(12)
	global_store_dwordx4 v[100:101], v[112:115], off
	v_lshlrev_b32_e32 v116, 16, v76
	v_and_b32_e32 v117, 0xffff0000, v76
	v_lshlrev_b32_e32 v118, 16, v77
	v_and_b32_e32 v119, 0xffff0000, v77
	v_lshlrev_b32_e32 v120, 16, v78
	v_and_b32_e32 v121, 0xffff0000, v78
	v_lshlrev_b32_e32 v122, 16, v79
	v_and_b32_e32 v123, 0xffff0000, v79
	v_pk_fma_f32 v[104:105], v[104:105], v[80:81], v[116:117]
	v_pk_fma_f32 v[106:107], v[106:107], v[82:83], v[118:119]
	v_pk_fma_f32 v[108:109], v[108:109], v[84:85], v[120:121]
	v_pk_fma_f32 v[110:111], v[110:111], v[86:87], v[122:123]
	v_lshl_add_u64 v[100:101], v[100:101], 0, v[46:47]
	global_load_dwordx4 v[76:79], v[42:43], off
	global_load_dwordx4 v[80:83], v[44:45], off
	global_load_dwordx4 v[84:87], v[44:45], off offset:16
	v_lshl_add_u64 v[42:43], v[42:43], 0, v[46:47]
	v_lshl_add_u64 v[44:45], v[44:45], 0, v[50:51]
	v_cvt_pk_bf16_f32 v112, v104, v105
	v_cvt_pk_bf16_f32 v113, v106, v107
	v_cvt_pk_bf16_f32 v114, v108, v109
	v_cvt_pk_bf16_f32 v115, v110, v111
	s_waitcnt vmcnt(12)
	global_store_dwordx4 v[100:101], v[112:115], off
	v_lshlrev_b32_e32 v116, 16, v88
	v_and_b32_e32 v117, 0xffff0000, v88
	v_lshlrev_b32_e32 v118, 16, v89
	v_and_b32_e32 v119, 0xffff0000, v89
	v_lshlrev_b32_e32 v120, 16, v90
	v_and_b32_e32 v121, 0xffff0000, v90
	v_lshlrev_b32_e32 v122, 16, v91
	v_and_b32_e32 v123, 0xffff0000, v91
	v_pk_fma_f32 v[104:105], v[104:105], v[92:93], v[116:117]
	v_pk_fma_f32 v[106:107], v[106:107], v[94:95], v[118:119]
	v_pk_fma_f32 v[108:109], v[108:109], v[96:97], v[120:121]
	v_pk_fma_f32 v[110:111], v[110:111], v[98:99], v[122:123]
	v_lshl_add_u64 v[100:101], v[100:101], 0, v[46:47]
	global_load_dwordx4 v[88:91], v[42:43], off
	global_load_dwordx4 v[92:95], v[44:45], off
	global_load_dwordx4 v[96:99], v[44:45], off offset:16
	v_lshl_add_u64 v[42:43], v[42:43], 0, v[46:47]
	v_lshl_add_u64 v[44:45], v[44:45], 0, v[50:51]
	s_sub_i32 s7, s7, 1
	s_cmp_lg_u32 s7, 0
	s_cbranch_scc1 .Lscan_pipe
	v_add_u32_e32 v28, s77, v28
	v_cmp_lt_i32_e32 vcc, s6, v28
	s_or_b64 s[4:5], vcc, s[4:5]
	s_andn2_b64 exec, exec, s[4:5]
	s_cbranch_execnz .LBB0_555
